# P11 attention: a wave whose rows all have carry==0 skips QK/weights/PV of the remaining tiles (v54 + attnwskip)
# speedup vs baseline: 1.0070x; 1.0052x over previous
.LBB0_1340:
	v_cmp_eq_f32_e32 vcc, 0, v171
	s_nop 1
	s_cmp_eq_u64 vcc, exec
	s_cbranch_scc1 .LBB0_1346
	s_cmp_ge_i32 s12, s40
	s_cbranch_scc1 .LBB0_1346
	ds_read_b128 v[2:5], v204 offset:16384
	ds_read_b128 v[6:9], v204 offset:24576
	s_or_b32 s13, s12, 63
	s_mov_b64 s[10:11], -1
	s_cmp_lt_i32 s13, s39
	s_waitcnt lgkmcnt(1)
	v_mfma_f32_32x32x16_bf16 v[80:95], v[2:5], v[112:115], 0
	v_mbcnt_hi_u32_b32 v173, -1, v214
	s_waitcnt lgkmcnt(0)
	v_mfma_f32_32x32x16_bf16 v[96:111], v[6:9], v[112:115], 0
	ds_read_b128 v[2:5], v205 offset:16384
	ds_read_b128 v[6:9], v205 offset:24576
	s_waitcnt lgkmcnt(1)
	v_mfma_f32_32x32x16_bf16 v[80:95], v[2:5], v[116:119], v[80:95]
	s_waitcnt lgkmcnt(0)
	v_mfma_f32_32x32x16_bf16 v[96:111], v[6:9], v[116:119], v[96:111]
	ds_read_b128 v[2:5], v206 offset:16384
	ds_read_b128 v[6:9], v206 offset:24576
	s_waitcnt lgkmcnt(1)
	v_mfma_f32_32x32x16_bf16 v[80:95], v[2:5], v[120:123], v[80:95]
	s_waitcnt lgkmcnt(0)
	v_mfma_f32_32x32x16_bf16 v[96:111], v[6:9], v[120:123], v[96:111]
	ds_read_b128 v[2:5], v207 offset:16384
	ds_read_b128 v[6:9], v207 offset:24576
	s_waitcnt lgkmcnt(1)
	v_mfma_f32_32x32x16_bf16 v[80:95], v[2:5], v[124:127], v[80:95]
	s_waitcnt lgkmcnt(0)
	v_mfma_f32_32x32x16_bf16 v[96:111], v[6:9], v[124:127], v[96:111]
	ds_read_b128 v[2:5], v208 offset:16384
	ds_read_b128 v[6:9], v208 offset:24576
	s_waitcnt lgkmcnt(1)
	v_mfma_f32_32x32x16_bf16 v[80:95], v[2:5], v[128:131], v[80:95]
	ds_read_b128 v[2:5], v209 offset:24576
	s_waitcnt lgkmcnt(1)
	v_mfma_f32_32x32x16_bf16 v[96:111], v[6:9], v[128:131], v[96:111]
	s_waitcnt lgkmcnt(0)
	v_mfma_f32_32x32x16_bf16 v[96:111], v[2:5], v[132:135], v[96:111]
	ds_read_b128 v[2:5], v210 offset:24576
	s_waitcnt lgkmcnt(0)
	v_mfma_f32_32x32x16_bf16 v[96:111], v[2:5], v[136:139], v[96:111]
	ds_read_b128 v[2:5], v211 offset:24576
	ds_read_b128 v[6:9], v209 offset:16384
	ds_read_b128 v[10:13], v210 offset:16384
	s_waitcnt lgkmcnt(1)
	v_mfma_f32_32x32x16_bf16 v[80:95], v[6:9], v[132:135], v[80:95]
	v_mfma_f32_32x32x16_bf16 v[96:111], v[2:5], v[140:143], v[96:111]
	ds_read_b128 v[2:5], v211 offset:16384
	s_waitcnt lgkmcnt(1)
	v_mfma_f32_32x32x16_bf16 v[80:95], v[10:13], v[136:139], v[80:95]
	s_nop 8
	v_max_f32_e32 v224, v96, v96
	v_max_f32_e32 v223, v97, v97
	v_max_f32_e32 v222, v98, v98
	v_max_f32_e32 v221, v99, v99
	v_max_f32_e32 v220, v100, v100
	v_max_f32_e32 v219, v101, v101
	v_max_f32_e32 v218, v102, v102
	s_waitcnt lgkmcnt(0)
	v_mfma_f32_32x32x16_bf16 v[80:95], v[2:5], v[140:143], v[80:95]
	v_max_f32_e32 v217, v103, v103
	v_max_f32_e32 v216, v104, v104
	v_max_f32_e32 v215, v105, v105
	v_max_f32_e32 v185, v106, v106
	v_max_f32_e32 v183, v107, v107
	v_max_f32_e32 v181, v108, v108
	v_max_f32_e32 v179, v109, v109
	v_max_f32_e32 v177, v110, v110
	v_max_f32_e32 v175, v111, v111
	s_nop 2
	v_max_f32_e32 v111, v80, v80
	v_max_f32_e32 v109, v81, v81
	v_max_f32_e32 v110, v82, v82
	v_max_f32_e32 v108, v83, v83
	v_max_f32_e32 v107, v84, v84
	v_max_f32_e32 v106, v85, v85
	v_max_f32_e32 v105, v86, v86
	v_max_f32_e32 v104, v87, v87
	v_max_f32_e32 v103, v88, v88
	v_max_f32_e32 v102, v89, v89
	v_max_f32_e32 v101, v90, v90
	v_max_f32_e32 v100, v91, v91
	v_max_f32_e32 v99, v92, v92
	v_max_f32_e32 v98, v93, v93
	v_max_f32_e32 v82, v94, v94
	v_max_f32_e32 v1, v95, v95
	s_cbranch_scc1 .LBB0_1343
	v_min_f32_e32 v2, 0x42c80000, v224
	v_exp_f32_e32 v2, v2
	v_min_f32_e32 v3, 0x42c80000, v223
	v_exp_f32_e32 v3, v3
	v_or_b32_e32 v90, s12, v196
	v_add_f32_e32 v4, 1.0, v2
	v_rcp_f32_e32 v4, v4
	v_or_b32_e32 v5, 32, v90
	v_cmp_lt_i32_e32 vcc, v5, v186
	v_min_f32_e32 v5, 0x42c80000, v222
	v_mul_f32_e32 v2, v2, v4
	v_cndmask_b32_e32 v83, 0, v2, vcc
	v_add_f32_e32 v2, 1.0, v3
	v_rcp_f32_e32 v2, v2
	v_exp_f32_e32 v5, v5
	v_cndmask_b32_e32 v11, 1.0, v4, vcc
	v_or_b32_e32 v4, 33, v90
	v_cmp_lt_i32_e32 vcc, v4, v186
	v_min_f32_e32 v4, 0x42c80000, v221
	v_exp_f32_e32 v4, v4
	v_cndmask_b32_e32 v15, 1.0, v2, vcc
	v_mul_f32_e32 v2, v3, v2
	v_cndmask_b32_e32 v88, 0, v2, vcc
	v_add_f32_e32 v2, 1.0, v5
	v_rcp_f32_e32 v2, v2
	v_or_b32_e32 v3, 34, v90
	v_cmp_lt_i32_e32 vcc, v3, v186
	v_or_b32_e32 v3, 35, v90
	v_min_f32_e32 v97, 0x42c80000, v175
	v_cndmask_b32_e32 v81, 1.0, v2, vcc
	v_mul_f32_e32 v2, v5, v2
	v_cndmask_b32_e32 v89, 0, v2, vcc
	v_add_f32_e32 v2, 1.0, v4
	v_rcp_f32_e32 v2, v2
	v_min_f32_e32 v5, 0x42c80000, v220
	v_exp_f32_e32 v5, v5
	v_cmp_lt_i32_e32 vcc, v3, v186
	v_or_b32_e32 v3, 40, v90
	v_exp_f32_e32 v97, v97
	v_cndmask_b32_e32 v85, 1.0, v2, vcc
	v_mul_f32_e32 v2, v4, v2
	v_cndmask_b32_e32 v91, 0, v2, vcc
	v_add_f32_e32 v2, 1.0, v5
	v_rcp_f32_e32 v2, v2
	v_min_f32_e32 v4, 0x42c80000, v219
	v_exp_f32_e32 v4, v4
	v_cmp_lt_i32_e32 vcc, v3, v186
	v_or_b32_e32 v3, 41, v90
	v_add_f32_e32 v227, 1.0, v97
	v_cndmask_b32_e32 v8, 1.0, v2, vcc
	v_mul_f32_e32 v2, v5, v2
	v_cndmask_b32_e32 v92, 0, v2, vcc
	v_add_f32_e32 v2, 1.0, v4
	v_rcp_f32_e32 v2, v2
	v_min_f32_e32 v5, 0x42c80000, v218
	v_exp_f32_e32 v5, v5
	v_cmp_lt_i32_e32 vcc, v3, v186
	v_or_b32_e32 v3, 42, v90
	v_rcp_f32_e32 v227, v227
	v_cndmask_b32_e32 v86, 1.0, v2, vcc
	v_mul_f32_e32 v2, v4, v2
	v_cndmask_b32_e32 v93, 0, v2, vcc
	v_add_f32_e32 v2, 1.0, v5
	v_rcp_f32_e32 v2, v2
	v_min_f32_e32 v4, 0x42c80000, v217
	v_exp_f32_e32 v4, v4
	v_cmp_lt_i32_e32 vcc, v3, v186
	v_or_b32_e32 v3, 43, v90
	v_and_b32_e32 v230, 64, v173
	v_cndmask_b32_e32 v87, 1.0, v2, vcc
	v_mul_f32_e32 v2, v5, v2
	v_cndmask_b32_e32 v94, 0, v2, vcc
	v_add_f32_e32 v2, 1.0, v4
	v_rcp_f32_e32 v2, v2
	v_min_f32_e32 v5, 0x42c80000, v216
	v_exp_f32_e32 v5, v5
	v_cmp_lt_i32_e32 vcc, v3, v186
	v_or_b32_e32 v3, 48, v90
	v_or_b32_e32 v226, 58, v90
	v_cndmask_b32_e32 v95, 1.0, v2, vcc
	v_mul_f32_e32 v2, v4, v2
	v_cndmask_b32_e32 v96, 0, v2, vcc
	v_add_f32_e32 v2, 1.0, v5
	v_rcp_f32_e32 v2, v2
	v_min_f32_e32 v4, 0x42c80000, v215
	v_exp_f32_e32 v4, v4
	v_cmp_lt_i32_e32 vcc, v3, v186
	v_or_b32_e32 v3, 49, v90
	v_or_b32_e32 v228, 59, v90
	v_cndmask_b32_e32 v6, 1.0, v2, vcc
	v_mul_f32_e32 v2, v5, v2
	v_cndmask_b32_e32 v12, 0, v2, vcc
	v_add_f32_e32 v2, 1.0, v4
	v_rcp_f32_e32 v2, v2
	v_min_f32_e32 v5, 0x42c80000, v185
	v_exp_f32_e32 v5, v5
	v_cmp_lt_i32_e32 vcc, v3, v186
	v_or_b32_e32 v3, 50, v90
	v_xor_b32_e32 v229, 32, v173
	v_cndmask_b32_e32 v7, 1.0, v2, vcc
	v_mul_f32_e32 v2, v4, v2
	v_cndmask_b32_e32 v9, 0, v2, vcc
	v_add_f32_e32 v2, 1.0, v5
	v_rcp_f32_e32 v2, v2
	v_min_f32_e32 v4, 0x42c80000, v183
	v_exp_f32_e32 v4, v4
	v_cmp_lt_i32_e32 vcc, v3, v186
	v_or_b32_e32 v3, 51, v90
	v_add_u32_e32 v230, 64, v230
	v_cndmask_b32_e32 v10, 1.0, v2, vcc
	v_mul_f32_e32 v2, v5, v2
	v_cndmask_b32_e32 v13, 0, v2, vcc
	v_add_f32_e32 v2, 1.0, v4
	v_rcp_f32_e32 v2, v2
	v_min_f32_e32 v5, 0x42c80000, v181
	v_exp_f32_e32 v5, v5
	v_cmp_lt_i32_e32 vcc, v3, v186
	v_or_b32_e32 v3, 56, v90
	v_cmp_lt_i32_e64 s[10:11], v228, v186
	v_cndmask_b32_e32 v14, 1.0, v2, vcc
	v_mul_f32_e32 v2, v4, v2
	v_cndmask_b32_e32 v84, 0, v2, vcc
	v_add_f32_e32 v2, 1.0, v5
	v_min_f32_e32 v4, 0x42c80000, v179
	v_rcp_f32_e32 v2, v2
	v_exp_f32_e32 v4, v4
	v_cmp_lt_i32_e32 vcc, v3, v186
	v_cmp_lt_i32_e64 s[12:13], v229, v230
	v_cndmask_b32_e64 v228, 1.0, v227, s[10:11]
	v_cndmask_b32_e32 v3, 1.0, v2, vcc
	v_mul_f32_e32 v2, v5, v2
	v_add_f32_e32 v5, 1.0, v4
	v_rcp_f32_e32 v5, v5
	v_cndmask_b32_e32 v80, 0, v2, vcc
	v_or_b32_e32 v2, 57, v90
	v_cmp_lt_i32_e32 vcc, v2, v186
	v_mul_f32_e32 v4, v4, v5
	v_cndmask_b32_e64 v229, v173, v229, s[12:13]
	v_cndmask_b32_e32 v2, 1.0, v5, vcc
	v_min_f32_e32 v5, 0x42c80000, v177
	v_exp_f32_e32 v5, v5
	v_cndmask_b32_e32 v4, 0, v4, vcc
	v_cmp_lt_i32_e32 vcc, v226, v186
	v_lshlrev_b32_e32 v231, 2, v229
	v_add_f32_e32 v225, 1.0, v5
	v_rcp_f32_e32 v225, v225
	v_mul_f32_e32 v3, v3, v2
	v_mul_f32_e32 v8, v8, v86
	v_cndmask_b32_e32 v226, 1.0, v225, vcc
	v_mul_f32_e32 v229, v226, v228
	v_mul_f32_e32 v229, v3, v229
	ds_bpermute_b32 v230, v231, v229
	v_mul_f32_e32 v3, v5, v225
	v_cndmask_b32_e32 v5, 0, v3, vcc
	v_mul_f32_e32 v3, v97, v227
	v_cndmask_b32_e64 v3, 0, v3, s[10:11]
	s_waitcnt lgkmcnt(0)
	v_mul_f32_e32 v97, v171, v230
	v_cndmask_b32_e64 v97, v171, v97, s[6:7]
	v_mul_f32_e32 v225, v228, v97
	v_mul_f32_e32 v226, v226, v225
	v_mul_f32_e32 v227, v2, v226
	v_mul_f32_e32 v2, v5, v225
	v_mul_f32_e32 v5, v6, v7
	v_mul_f32_e32 v6, v10, v14
	v_mul_f32_e32 v3, v3, v97
	v_mul_f32_e32 v97, v5, v6
	ds_bpermute_b32 v225, v231, v97
	v_mul_f32_e32 v6, v229, v230
	v_mul_f32_e32 v5, v4, v226
	v_mul_f32_e32 v4, v80, v227
	v_mul_f32_e32 v80, v171, v6
	s_waitcnt lgkmcnt(0)
	v_mul_f32_e32 v6, v80, v225
	v_cndmask_b32_e64 v6, v80, v6, s[6:7]
	v_mul_f32_e32 v14, v14, v6
	v_mul_f32_e32 v226, v10, v14
	v_mul_f32_e32 v10, v87, v95
	v_mul_f32_e32 v10, v8, v10
	v_mul_f32_e32 v227, v7, v226
	v_mul_f32_e32 v7, v84, v6
	v_mul_f32_e32 v6, v13, v14
	ds_bpermute_b32 v14, v231, v10
	v_mul_f32_e32 v84, v97, v225
	v_mul_f32_e32 v8, v12, v227
	v_pk_mul_f32 v[12:13], v[80:81], v[84:85]
	v_cmp_lt_i32_e32 vcc, v90, v186
	s_waitcnt lgkmcnt(0)
	v_mul_f32_e32 v80, v12, v14
	v_cndmask_b32_e64 v80, v12, v80, s[6:7]
	v_mul_f32_e32 v84, v95, v80
	v_mul_f32_e32 v95, v87, v84
	v_pk_mul_f32 v[10:11], v[10:11], v[14:15]
	v_mul_f32_e32 v97, v86, v95
	v_pk_mul_f32 v[86:87], v[10:11], v[12:13]
	ds_bpermute_b32 v225, v231, v87
	v_mul_f32_e32 v11, v96, v80
	v_mul_f32_e32 v10, v94, v84
	v_mul_f32_e32 v9, v9, v226
	v_mul_f32_e32 v12, v92, v97
	s_waitcnt lgkmcnt(0)
	v_mul_f32_e32 v14, v86, v225
	v_cndmask_b32_e64 v14, v86, v14, s[6:7]
	v_mul_f32_e32 v80, v85, v14
	v_mul_f32_e32 v81, v81, v80
	v_mul_f32_e32 v84, v15, v81
	v_mul_f32_e32 v15, v91, v14
	v_mul_f32_e32 v14, v89, v80
	v_min_f32_e32 v80, 0x42c80000, v111
	v_exp_f32_e32 v85, v80
	v_mul_f32_e32 v80, v83, v84
	v_min_f32_e32 v84, 0x42c80000, v109
	v_exp_f32_e32 v84, v84
	v_add_f32_e32 v83, 1.0, v85
	v_rcp_f32_e32 v83, v83
	v_mul_f32_e32 v81, v88, v81
	v_mul_f32_e32 v88, v87, v225
	v_min_f32_e32 v87, 0x42c80000, v110
	v_cndmask_b32_e32 v245, 1.0, v83, vcc
	v_mul_f32_e32 v83, v85, v83
	v_cndmask_b32_e32 v225, 0, v83, vcc
	v_add_f32_e32 v83, 1.0, v84
	v_rcp_f32_e32 v85, v83
	v_exp_f32_e32 v87, v87
	v_or_b32_e32 v83, 1, v90
	v_cmp_lt_i32_e32 vcc, v83, v186
	v_mul_f32_e32 v84, v84, v85
	v_min_f32_e32 v89, 0x42c80000, v108
	v_cndmask_b32_e32 v230, 0, v84, vcc
	v_add_f32_e32 v84, 1.0, v87
	v_rcp_f32_e32 v84, v84
	v_cndmask_b32_e32 v83, 1.0, v85, vcc
	v_or_b32_e32 v85, 2, v90
	v_exp_f32_e32 v89, v89
	v_cmp_lt_i32_e32 vcc, v85, v186
	v_or_b32_e32 v85, 3, v90
	v_mul_f32_e32 v13, v93, v95
	v_cndmask_b32_e32 v226, 1.0, v84, vcc
	v_mul_f32_e32 v84, v87, v84
	v_min_f32_e32 v87, 0x42c80000, v107
	v_exp_f32_e32 v87, v87
	v_cndmask_b32_e32 v227, 0, v84, vcc
	v_add_f32_e32 v84, 1.0, v89
	v_rcp_f32_e32 v84, v84
	v_cmp_lt_i32_e32 vcc, v85, v186
	v_add_f32_e32 v85, 1.0, v87
	v_rcp_f32_e32 v85, v85
	v_cndmask_b32_e32 v228, 1.0, v84, vcc
	v_mul_f32_e32 v84, v89, v84
	v_cndmask_b32_e32 v229, 0, v84, vcc
	v_or_b32_e32 v84, 8, v90
	v_cmp_lt_i32_e32 vcc, v84, v186
	v_mul_f32_e32 v84, v87, v85
	v_or_b32_e32 v89, 11, v90
	v_cndmask_b32_e32 v97, 1.0, v85, vcc
	v_min_f32_e32 v85, 0x42c80000, v106
	v_exp_f32_e32 v92, v85
	v_min_f32_e32 v85, 0x42c80000, v105
	v_cndmask_b32_e32 v96, 0, v84, vcc
	v_exp_f32_e32 v93, v85
	v_add_f32_e32 v84, 1.0, v92
	v_rcp_f32_e32 v94, v84
	v_min_f32_e32 v84, 0x42c80000, v104
	v_exp_f32_e32 v84, v84
	v_min_f32_e32 v85, 0x42c80000, v103
	v_exp_f32_e32 v85, v85
	v_add_f32_e32 v87, 1.0, v93
	v_rcp_f32_e32 v95, v87
	v_add_f32_e32 v87, 1.0, v84
	v_rcp_f32_e32 v232, v87
	v_add_f32_e32 v87, 1.0, v85
	v_rcp_f32_e32 v233, v87
	v_or_b32_e32 v87, 16, v90
	v_cmp_lt_i32_e64 s[10:11], v87, v169
	v_min_f32_e32 v87, 0x42c80000, v100
	v_exp_f32_e32 v238, v87
	v_min_f32_e32 v87, 0x42c80000, v99
	v_exp_f32_e32 v239, v87
	v_cmp_lt_i32_e32 vcc, v89, v186
	v_add_f32_e32 v87, 1.0, v238
	v_rcp_f32_e32 v240, v87
	v_add_f32_e32 v87, 1.0, v239
	v_rcp_f32_e32 v241, v87
	v_pk_mul_f32 v[84:85], v[84:85], v[232:233]
	v_or_b32_e32 v89, 19, v90
	v_cndmask_b32_e32 v247, 1.0, v232, vcc
	v_cndmask_b32_e32 v232, 0, v84, vcc
	v_or_b32_e32 v87, 24, v90
	v_cmp_lt_i32_e32 vcc, v89, v186
	v_min_f32_e32 v91, 0x42c80000, v98
	v_cndmask_b32_e64 v235, 1.0, v233, s[10:11]
	v_cndmask_b32_e64 v233, 0, v85, s[10:11]
	v_cndmask_b32_e32 v89, 1.0, v240, vcc
	v_cmp_lt_i32_e64 s[10:11], v87, v169
	v_pk_mul_f32 v[238:239], v[238:239], v[240:241]
	v_exp_f32_e32 v240, v91
	v_min_f32_e32 v91, 0x42c80000, v82
	v_cndmask_b32_e64 v87, 1.0, v241, s[10:11]
	v_exp_f32_e32 v241, v91
	v_min_f32_e32 v91, 0x42c80000, v1
	v_exp_f32_e32 v91, v91
	v_add_f32_e32 v234, 1.0, v240
	v_rcp_f32_e32 v242, v234
	v_add_f32_e32 v234, 1.0, v241
	v_add_f32_e32 v243, 1.0, v91
	v_rcp_f32_e32 v244, v243
	v_min_f32_e32 v85, 0x42c80000, v102
	v_rcp_f32_e32 v243, v234
	v_or_b32_e32 v234, 27, v90
	v_exp_f32_e32 v236, v85
	v_min_f32_e32 v85, 0x42c80000, v101
	v_cndmask_b32_e32 v238, 0, v238, vcc
	v_cmp_lt_i32_e32 vcc, v234, v186
	v_mul_f32_e32 v91, v91, v244
	v_exp_f32_e32 v237, v85
	v_cndmask_b32_e32 v248, 1.0, v244, vcc
	v_cndmask_b32_e32 v244, 0, v91, vcc
	v_or_b32_e32 v91, 26, v90
	v_or_b32_e32 v234, 25, v90
	v_cndmask_b32_e64 v239, 0, v239, s[10:11]
	v_cmp_lt_i32_e32 vcc, v234, v186
	v_cmp_lt_i32_e64 s[10:11], v91, v169
	v_add_f32_e32 v84, 1.0, v236
	v_cndmask_b32_e32 v249, 1.0, v242, vcc
	v_cndmask_b32_e64 v91, 1.0, v243, s[10:11]
	v_mul_f32_e32 v87, v87, v249
	v_mul_f32_e32 v234, v91, v248
	v_add_f32_e32 v85, 1.0, v237
	v_mul_f32_e32 v234, v87, v234
	v_rcp_f32_e32 v84, v84
	v_rcp_f32_e32 v85, v85
	v_pk_mul_f32 v[240:241], v[240:241], v[242:243]
	ds_bpermute_b32 v242, v231, v234
	v_or_b32_e32 v87, 18, v90
	v_or_b32_e32 v243, 17, v90
	v_cndmask_b32_e64 v241, 0, v241, s[10:11]
	v_cndmask_b32_e32 v240, 0, v240, vcc
	v_cmp_lt_i32_e32 vcc, v243, v186
	v_cmp_lt_i32_e64 s[10:11], v87, v169
	v_pk_mul_f32 v[92:93], v[92:93], v[94:95]
	v_cndmask_b32_e32 v243, 1.0, v84, vcc
	v_cndmask_b32_e64 v87, 1.0, v85, s[10:11]
	v_pk_mul_f32 v[84:85], v[236:237], v[84:85]
	s_waitcnt lgkmcnt(0)
	v_pk_mul_f32 v[234:235], v[234:235], v[242:243]
	v_cndmask_b32_e64 v237, 0, v85, s[10:11]
	v_cndmask_b32_e32 v236, 0, v84, vcc
	v_pk_mul_f32 v[84:85], v[86:87], v[88:89]
	v_mul_f32_e32 v245, v245, v83
	v_pk_mul_f32 v[234:235], v[234:235], v[84:85]
	v_mul_f32_e32 v86, v84, v242
	ds_bpermute_b32 v242, v231, v235
	v_cndmask_b32_e64 v246, v84, v86, s[6:7]
	v_mul_f32_e32 v85, v248, v246
	v_mul_f32_e32 v84, v91, v85
	v_mul_f32_e32 v249, v249, v84
	s_waitcnt lgkmcnt(0)
	v_mul_f32_e32 v86, v234, v242
	v_cndmask_b32_e64 v248, v234, v86, s[6:7]
	v_mul_f32_e32 v89, v89, v248
	v_mul_f32_e32 v88, v87, v89
	v_mul_f32_e32 v91, v243, v88
	v_pk_mul_f32 v[88:89], v[236:237], v[88:89]
	v_or_b32_e32 v237, 10, v90
	v_or_b32_e32 v90, 9, v90
	v_cmp_lt_i32_e32 vcc, v90, v186
	v_cmp_lt_i32_e64 s[10:11], v237, v169
	v_pk_mul_f32 v[86:87], v[238:239], v[248:249]
	v_cndmask_b32_e32 v236, 1.0, v94, vcc
	v_cndmask_b32_e64 v238, 1.0, v95, s[10:11]
	v_mul_f32_e32 v90, v97, v236
	v_mul_f32_e32 v97, v238, v247
	v_mul_f32_e32 v239, v90, v97
	ds_bpermute_b32 v237, v231, v239
	v_mul_f32_e32 v235, v235, v242
	v_mul_f32_e32 v97, v234, v235
	v_cndmask_b32_e64 v93, 0, v93, s[10:11]
	v_cndmask_b32_e32 v92, 0, v92, vcc
	s_waitcnt lgkmcnt(0)
	v_mul_f32_e32 v90, v97, v237
	v_cndmask_b32_e64 v90, v97, v90, s[6:7]
	v_mul_f32_e32 v235, v247, v90
	v_mul_f32_e32 v234, v238, v235
	v_mul_f32_e32 v247, v226, v228
	v_pk_mul_f32 v[94:95], v[92:93], v[234:235]
	v_pk_mul_f32 v[92:93], v[244:245], v[246:247]
	ds_bpermute_b32 v231, v231, v93
	v_mov_b32_e32 v235, v239
	v_pk_mul_f32 v[90:91], v[232:233], v[90:91]
	v_pk_mul_f32 v[232:233], v[234:235], v[236:237]
	v_pk_mul_f32 v[84:85], v[240:241], v[84:85]
	v_pk_mul_f32 v[96:97], v[96:97], v[232:233]
	s_mov_b64 s[10:11], 0
